# P14 K loop: LDS-DMA loads use SGPR base + 32-bit lane offset (no per-load VALU address arithmetic)
# baseline (speedup 1.0000x reference)
.LBB0_1706:
	ds_read_b128 v[130:133], v213
	ds_read_b128 v[134:137], v213 offset:1024
	ds_read_b128 v[138:141], v213 offset:2048
	ds_read_b128 v[142:145], v213 offset:3072
	ds_read_b128 v[178:181], v215
	ds_read_b128 v[182:185], v215 offset:1024
	ds_read_b128 v[186:189], v215 offset:2048
	ds_read_b128 v[190:193], v215 offset:3072
	s_add_u32 s0, s60, 0xfffc0080
	s_addc_u32 s1, s61, -1
	s_cmp_eq_u32 s86, 12
	s_cselect_b32 s1, s9, s1
	s_cselect_b32 s0, s8, s0
	s_cselect_b32 s31, s59, s63
	s_cselect_b32 s30, s58, s62
	ds_read_b128 v[146:149], v214
	ds_read_b128 v[150:153], v214 offset:1024
	ds_read_b128 v[154:157], v214 offset:2048
	ds_read_b128 v[158:161], v214 offset:3072
	ds_read_b128 v[162:165], v214 offset:4096
	ds_read_b128 v[166:169], v214 offset:5120
	ds_read_b128 v[170:173], v214 offset:6144
	ds_read_b128 v[174:177], v214 offset:7168
	s_add_i32 m0, s6, 0xc000
	s_nop 0
	global_load_lds_dwordx4 v198, s[60:61]
	s_add_u32 s100, s60, s10
	s_addc_u32 s101, s61, s11
	s_add_i32 m0, s6, 0xe000
	s_nop 0
	global_load_lds_dwordx4 v198, s[100:101]
	s_cmp_lg_u32 s98, 0
	s_cbranch_scc1 .Lsk1_p14
	s_waitcnt vmcnt(8)
.Lsk1_p14:
	s_waitcnt lgkmcnt(0)
	s_barrier
	s_setprio 1
	v_mfma_f32_16x16x32_bf16 v[126:129], v[130:133], v[146:149], v[126:129]
	v_mfma_f32_16x16x32_bf16 v[122:125], v[138:141], v[146:149], v[122:125]
	v_mfma_f32_16x16x32_bf16 v[118:121], v[130:133], v[154:157], v[118:121]
	v_mfma_f32_16x16x32_bf16 v[114:117], v[138:141], v[154:157], v[114:117]
	v_mfma_f32_16x16x32_bf16 v[110:113], v[130:133], v[162:165], v[110:113]
	v_mfma_f32_16x16x32_bf16 v[106:109], v[138:141], v[162:165], v[106:109]
	v_mfma_f32_16x16x32_bf16 v[102:105], v[130:133], v[170:173], v[102:105]
	v_mfma_f32_16x16x32_bf16 v[98:101], v[138:141], v[170:173], v[98:101]
	v_mfma_f32_16x16x32_bf16 v[126:129], v[134:137], v[150:153], v[126:129]
	v_mfma_f32_16x16x32_bf16 v[122:125], v[142:145], v[150:153], v[122:125]
	v_mfma_f32_16x16x32_bf16 v[118:121], v[134:137], v[158:161], v[118:121]
	v_mfma_f32_16x16x32_bf16 v[114:117], v[142:145], v[158:161], v[114:117]
	v_mfma_f32_16x16x32_bf16 v[110:113], v[134:137], v[166:169], v[110:113]
	v_mfma_f32_16x16x32_bf16 v[106:109], v[142:145], v[166:169], v[106:109]
	v_mfma_f32_16x16x32_bf16 v[102:105], v[134:137], v[174:177], v[102:105]
	v_mfma_f32_16x16x32_bf16 v[98:101], v[142:145], v[174:177], v[98:101]
	v_mfma_f32_16x16x32_bf16 v[62:65], v[178:181], v[146:149], v[62:65]
	v_mfma_f32_16x16x32_bf16 v[58:61], v[186:189], v[146:149], v[58:61]
	v_mfma_f32_16x16x32_bf16 v[54:57], v[178:181], v[154:157], v[54:57]
	v_mfma_f32_16x16x32_bf16 v[50:53], v[186:189], v[154:157], v[50:53]
	v_mfma_f32_16x16x32_bf16 v[46:49], v[178:181], v[162:165], v[46:49]
	v_mfma_f32_16x16x32_bf16 v[42:45], v[186:189], v[162:165], v[42:45]
	v_mfma_f32_16x16x32_bf16 v[38:41], v[178:181], v[170:173], v[38:41]
	v_mfma_f32_16x16x32_bf16 v[34:37], v[186:189], v[170:173], v[34:37]
	v_mfma_f32_16x16x32_bf16 v[62:65], v[182:185], v[150:153], v[62:65]
	v_mfma_f32_16x16x32_bf16 v[58:61], v[190:193], v[150:153], v[58:61]
	v_mfma_f32_16x16x32_bf16 v[54:57], v[182:185], v[158:161], v[54:57]
	v_mfma_f32_16x16x32_bf16 v[50:53], v[190:193], v[158:161], v[50:53]
	v_mfma_f32_16x16x32_bf16 v[46:49], v[182:185], v[166:169], v[46:49]
	v_mfma_f32_16x16x32_bf16 v[42:45], v[190:193], v[166:169], v[42:45]
	v_mfma_f32_16x16x32_bf16 v[38:41], v[182:185], v[174:177], v[38:41]
	v_mfma_f32_16x16x32_bf16 v[34:37], v[190:193], v[174:177], v[34:37]
	s_setprio 0
	s_barrier
	ds_read_b128 v[146:149], v214 offset:16384
	ds_read_b128 v[150:153], v214 offset:17408
	ds_read_b128 v[154:157], v214 offset:18432
	ds_read_b128 v[158:161], v214 offset:19456
	ds_read_b128 v[162:165], v214 offset:20480
	ds_read_b128 v[166:169], v214 offset:21504
	ds_read_b128 v[170:173], v214 offset:22528
	ds_read_b128 v[174:177], v214 offset:23552
	s_add_i32 s99, s73, s5
	s_mov_b32 m0, s99
	s_nop 0
	global_load_lds_dwordx4 v196, s[30:31]
	s_add_u32 s100, s30, s10
	s_addc_u32 s101, s31, s11
	s_add_i32 m0, s99, 0x2000
	s_nop 0
	global_load_lds_dwordx4 v196, s[100:101]
	s_add_i32 s99, s74, s5
	s_add_u32 s100, s30, s16
	s_addc_u32 s101, s31, s17
	s_mov_b32 m0, s99
	s_nop 0
	global_load_lds_dwordx4 v196, s[100:101]
	s_add_u32 s100, s30, s18
	s_addc_u32 s101, s31, s19
	s_add_i32 m0, s99, 0x2000
	s_nop 0
	global_load_lds_dwordx4 v196, s[100:101]
	s_mov_b32 m0, s6
	s_nop 0
	global_load_lds_dwordx4 v194, s[0:1]
	s_add_u32 s100, s0, s10
	s_addc_u32 s101, s1, s11
	s_mov_b32 m0, s7
	s_nop 0
	global_load_lds_dwordx4 v194, s[100:101]
	s_cmp_lg_u32 s98, 0
	s_cbranch_scc1 .Lsk2_p14
	s_waitcnt vmcnt(8)
.Lsk2_p14:
	s_mov_b32 s98, 0
	s_waitcnt lgkmcnt(0)
	s_barrier
	s_setprio 1
	v_mfma_f32_16x16x32_bf16 v[94:97], v[130:133], v[146:149], v[94:97]
	v_mfma_f32_16x16x32_bf16 v[90:93], v[138:141], v[146:149], v[90:93]
	v_mfma_f32_16x16x32_bf16 v[86:89], v[130:133], v[154:157], v[86:89]
	v_mfma_f32_16x16x32_bf16 v[82:85], v[138:141], v[154:157], v[82:85]
	v_mfma_f32_16x16x32_bf16 v[78:81], v[130:133], v[162:165], v[78:81]
	v_mfma_f32_16x16x32_bf16 v[74:77], v[138:141], v[162:165], v[74:77]
	v_mfma_f32_16x16x32_bf16 v[70:73], v[130:133], v[170:173], v[70:73]
	v_mfma_f32_16x16x32_bf16 v[66:69], v[138:141], v[170:173], v[66:69]
	v_mfma_f32_16x16x32_bf16 v[94:97], v[134:137], v[150:153], v[94:97]
	v_mfma_f32_16x16x32_bf16 v[90:93], v[142:145], v[150:153], v[90:93]
	v_mfma_f32_16x16x32_bf16 v[86:89], v[134:137], v[158:161], v[86:89]
	v_mfma_f32_16x16x32_bf16 v[82:85], v[142:145], v[158:161], v[82:85]
	v_mfma_f32_16x16x32_bf16 v[78:81], v[134:137], v[166:169], v[78:81]
	v_mfma_f32_16x16x32_bf16 v[74:77], v[142:145], v[166:169], v[74:77]
	v_mfma_f32_16x16x32_bf16 v[70:73], v[134:137], v[174:177], v[70:73]
	v_mfma_f32_16x16x32_bf16 v[66:69], v[142:145], v[174:177], v[66:69]
	v_mfma_f32_16x16x32_bf16 v[30:33], v[178:181], v[146:149], v[30:33]
	v_mfma_f32_16x16x32_bf16 v[26:29], v[186:189], v[146:149], v[26:29]
	v_mfma_f32_16x16x32_bf16 v[22:25], v[178:181], v[154:157], v[22:25]
	v_mfma_f32_16x16x32_bf16 v[18:21], v[186:189], v[154:157], v[18:21]
	v_mfma_f32_16x16x32_bf16 v[14:17], v[178:181], v[162:165], v[14:17]
	v_mfma_f32_16x16x32_bf16 v[10:13], v[186:189], v[162:165], v[10:13]
	v_mfma_f32_16x16x32_bf16 v[6:9], v[178:181], v[170:173], v[6:9]
	v_mfma_f32_16x16x32_bf16 v[2:5], v[186:189], v[170:173], v[2:5]
	v_mfma_f32_16x16x32_bf16 v[30:33], v[182:185], v[150:153], v[30:33]
	v_mfma_f32_16x16x32_bf16 v[26:29], v[190:193], v[150:153], v[26:29]
	v_mfma_f32_16x16x32_bf16 v[22:25], v[182:185], v[158:161], v[22:25]
	v_mfma_f32_16x16x32_bf16 v[18:21], v[190:193], v[158:161], v[18:21]
	v_mfma_f32_16x16x32_bf16 v[14:17], v[182:185], v[166:169], v[14:17]
	v_mfma_f32_16x16x32_bf16 v[10:13], v[190:193], v[166:169], v[10:13]
	v_mfma_f32_16x16x32_bf16 v[6:9], v[182:185], v[174:177], v[6:9]
	v_mfma_f32_16x16x32_bf16 v[2:5], v[190:193], v[174:177], v[2:5]
	s_setprio 0
	v_add_u32_e32 v142, 0x18000, v212
	s_barrier
	v_add_u32_e32 v190, 0x1c000, v212
	ds_read_b128 v[130:133], v142
	ds_read_b128 v[134:137], v142 offset:1024
	ds_read_b128 v[138:141], v142 offset:2048
	ds_read_b128 v[142:145], v142 offset:3072
	ds_read_b128 v[178:181], v190
	ds_read_b128 v[182:185], v190 offset:1024
	ds_read_b128 v[186:189], v190 offset:2048
	ds_read_b128 v[190:193], v190 offset:3072
	ds_read_b128 v[146:149], v214 offset:32768
	ds_read_b128 v[150:153], v214 offset:33792
	ds_read_b128 v[154:157], v214 offset:34816
	ds_read_b128 v[158:161], v214 offset:35840
	ds_read_b128 v[162:165], v214 offset:36864
	ds_read_b128 v[166:169], v214 offset:37888
	ds_read_b128 v[170:173], v214 offset:38912
	ds_read_b128 v[174:177], v214 offset:39936
	s_add_u32 s100, s0, s16
	s_addc_u32 s101, s1, s17
	s_mov_b32 m0, s24
	s_nop 0
	global_load_lds_dwordx4 v194, s[100:101]
	s_add_u32 s100, s0, s18
	s_addc_u32 s101, s1, s19
	s_mov_b32 m0, s25
	s_nop 0
	global_load_lds_dwordx4 v194, s[100:101]
	s_waitcnt vmcnt(8)
	s_waitcnt lgkmcnt(0)
	s_barrier
	s_setprio 1
	v_mfma_f32_16x16x32_bf16 v[126:129], v[130:133], v[146:149], v[126:129]
	v_mfma_f32_16x16x32_bf16 v[122:125], v[138:141], v[146:149], v[122:125]
	v_mfma_f32_16x16x32_bf16 v[118:121], v[130:133], v[154:157], v[118:121]
	v_mfma_f32_16x16x32_bf16 v[114:117], v[138:141], v[154:157], v[114:117]
	v_mfma_f32_16x16x32_bf16 v[110:113], v[130:133], v[162:165], v[110:113]
	v_mfma_f32_16x16x32_bf16 v[106:109], v[138:141], v[162:165], v[106:109]
	v_mfma_f32_16x16x32_bf16 v[102:105], v[130:133], v[170:173], v[102:105]
	v_mfma_f32_16x16x32_bf16 v[98:101], v[138:141], v[170:173], v[98:101]
	v_mfma_f32_16x16x32_bf16 v[126:129], v[134:137], v[150:153], v[126:129]
	v_mfma_f32_16x16x32_bf16 v[122:125], v[142:145], v[150:153], v[122:125]
	v_mfma_f32_16x16x32_bf16 v[118:121], v[134:137], v[158:161], v[118:121]
	v_mfma_f32_16x16x32_bf16 v[114:117], v[142:145], v[158:161], v[114:117]
	v_mfma_f32_16x16x32_bf16 v[110:113], v[134:137], v[166:169], v[110:113]
	v_mfma_f32_16x16x32_bf16 v[106:109], v[142:145], v[166:169], v[106:109]
	v_mfma_f32_16x16x32_bf16 v[102:105], v[134:137], v[174:177], v[102:105]
	v_mfma_f32_16x16x32_bf16 v[98:101], v[142:145], v[174:177], v[98:101]
	v_mfma_f32_16x16x32_bf16 v[62:65], v[178:181], v[146:149], v[62:65]
	v_mfma_f32_16x16x32_bf16 v[58:61], v[186:189], v[146:149], v[58:61]
	v_mfma_f32_16x16x32_bf16 v[54:57], v[178:181], v[154:157], v[54:57]
	v_mfma_f32_16x16x32_bf16 v[50:53], v[186:189], v[154:157], v[50:53]
	v_mfma_f32_16x16x32_bf16 v[46:49], v[178:181], v[162:165], v[46:49]
	v_mfma_f32_16x16x32_bf16 v[42:45], v[186:189], v[162:165], v[42:45]
	v_mfma_f32_16x16x32_bf16 v[38:41], v[178:181], v[170:173], v[38:41]
	v_mfma_f32_16x16x32_bf16 v[34:37], v[186:189], v[170:173], v[34:37]
	v_mfma_f32_16x16x32_bf16 v[62:65], v[182:185], v[150:153], v[62:65]
	v_mfma_f32_16x16x32_bf16 v[58:61], v[190:193], v[150:153], v[58:61]
	v_mfma_f32_16x16x32_bf16 v[54:57], v[182:185], v[158:161], v[54:57]
	v_mfma_f32_16x16x32_bf16 v[50:53], v[190:193], v[158:161], v[50:53]
	v_mfma_f32_16x16x32_bf16 v[46:49], v[182:185], v[166:169], v[46:49]
	v_mfma_f32_16x16x32_bf16 v[42:45], v[190:193], v[166:169], v[42:45]
	v_mfma_f32_16x16x32_bf16 v[38:41], v[182:185], v[174:177], v[38:41]
	v_mfma_f32_16x16x32_bf16 v[34:37], v[190:193], v[174:177], v[34:37]
	s_setprio 0
	s_barrier
	ds_read_b128 v[146:149], v214 offset:49152
	ds_read_b128 v[150:153], v214 offset:50176
	ds_read_b128 v[154:157], v214 offset:51200
	ds_read_b128 v[158:161], v214 offset:52224
	ds_read_b128 v[162:165], v214 offset:53248
	ds_read_b128 v[166:169], v214 offset:54272
	ds_read_b128 v[170:173], v214 offset:55296
	ds_read_b128 v[174:177], v214 offset:56320
	s_add_i32 s99, s5, 0x18000
	s_add_u32 s100, s30, s38
	s_addc_u32 s101, s31, s39
	s_mov_b32 m0, s99
	s_nop 0
	global_load_lds_dwordx4 v196, s[100:101]
	s_add_u32 s100, s30, s40
	s_addc_u32 s101, s31, s41
	s_add_i32 m0, s99, 0x2000
	s_nop 0
	global_load_lds_dwordx4 v196, s[100:101]
	s_add_i32 s99, s5, 0x1c000
	s_add_u32 s100, s30, s42
	s_addc_u32 s101, s31, s43
	s_mov_b32 m0, s99
	s_nop 0
	global_load_lds_dwordx4 v196, s[100:101]
	s_add_u32 s100, s30, s44
	s_addc_u32 s101, s31, s45
	s_add_i32 m0, s99, 0x2000
	s_nop 0
	global_load_lds_dwordx4 v196, s[100:101]
	s_add_u32 s100, s0, s38
	s_addc_u32 s101, s1, s39
	s_mov_b32 m0, s65
	s_nop 0
	global_load_lds_dwordx4 v194, s[100:101]
	s_add_u32 s100, s0, s40
	s_addc_u32 s101, s1, s41
	s_mov_b32 m0, s66
	s_nop 0
	global_load_lds_dwordx4 v194, s[100:101]
	s_waitcnt vmcnt(8)
	s_waitcnt lgkmcnt(0)
	s_barrier
	s_setprio 1
	v_mfma_f32_16x16x32_bf16 v[94:97], v[130:133], v[146:149], v[94:97]
	v_mfma_f32_16x16x32_bf16 v[90:93], v[138:141], v[146:149], v[90:93]
	v_mfma_f32_16x16x32_bf16 v[86:89], v[130:133], v[154:157], v[86:89]
	v_mfma_f32_16x16x32_bf16 v[82:85], v[138:141], v[154:157], v[82:85]
	v_mfma_f32_16x16x32_bf16 v[78:81], v[130:133], v[162:165], v[78:81]
	v_mfma_f32_16x16x32_bf16 v[74:77], v[138:141], v[162:165], v[74:77]
	v_mfma_f32_16x16x32_bf16 v[70:73], v[130:133], v[170:173], v[70:73]
	v_mfma_f32_16x16x32_bf16 v[66:69], v[138:141], v[170:173], v[66:69]
	v_mfma_f32_16x16x32_bf16 v[94:97], v[134:137], v[150:153], v[94:97]
	v_mfma_f32_16x16x32_bf16 v[90:93], v[142:145], v[150:153], v[90:93]
	v_mfma_f32_16x16x32_bf16 v[86:89], v[134:137], v[158:161], v[86:89]
	v_mfma_f32_16x16x32_bf16 v[82:85], v[142:145], v[158:161], v[82:85]
	v_mfma_f32_16x16x32_bf16 v[78:81], v[134:137], v[166:169], v[78:81]
	v_mfma_f32_16x16x32_bf16 v[74:77], v[142:145], v[166:169], v[74:77]
	v_mfma_f32_16x16x32_bf16 v[70:73], v[134:137], v[174:177], v[70:73]
	v_mfma_f32_16x16x32_bf16 v[66:69], v[142:145], v[174:177], v[66:69]
	v_mfma_f32_16x16x32_bf16 v[30:33], v[178:181], v[146:149], v[30:33]
	v_mfma_f32_16x16x32_bf16 v[26:29], v[186:189], v[146:149], v[26:29]
	v_mfma_f32_16x16x32_bf16 v[22:25], v[178:181], v[154:157], v[22:25]
	v_mfma_f32_16x16x32_bf16 v[18:21], v[186:189], v[154:157], v[18:21]
	v_mfma_f32_16x16x32_bf16 v[14:17], v[178:181], v[162:165], v[14:17]
	v_mfma_f32_16x16x32_bf16 v[10:13], v[186:189], v[162:165], v[10:13]
	v_mfma_f32_16x16x32_bf16 v[6:9], v[178:181], v[170:173], v[6:9]
	v_mfma_f32_16x16x32_bf16 v[2:5], v[186:189], v[170:173], v[2:5]
	v_mfma_f32_16x16x32_bf16 v[30:33], v[182:185], v[150:153], v[30:33]
	v_mfma_f32_16x16x32_bf16 v[26:29], v[190:193], v[150:153], v[26:29]
	v_mfma_f32_16x16x32_bf16 v[22:25], v[182:185], v[158:161], v[22:25]
	v_mfma_f32_16x16x32_bf16 v[18:21], v[190:193], v[158:161], v[18:21]
	v_mfma_f32_16x16x32_bf16 v[14:17], v[182:185], v[166:169], v[14:17]
	v_mfma_f32_16x16x32_bf16 v[10:13], v[190:193], v[166:169], v[10:13]
	v_mfma_f32_16x16x32_bf16 v[6:9], v[182:185], v[174:177], v[6:9]
	v_mfma_f32_16x16x32_bf16 v[2:5], v[190:193], v[174:177], v[2:5]
	s_setprio 0
	s_add_i32 s86, s86, 2
	s_add_u32 s62, s62, 0x100
	s_addc_u32 s63, s63, 0
	s_add_u32 s60, s60, 0x100
	s_addc_u32 s61, s61, 0
	s_cmp_gt_u32 s86, 13
	s_barrier
	s_cbranch_scc0 .LBB0_1706
	s_mov_b32 s98, 1
	s_and_b64 vcc, exec, s[46:47]
	s_cbranch_vccz .LBB0_1709
	s_barrier
